# attA work queue: thread 0 issues the pop of the next unit at the start of the current unit's epilogue (result held in v241), loop-back path consumes it instead of a fresh atomic; on top of lean mask +
# baseline (speedup 1.0000x reference)
; __global__ void __launch_bounds__(NTHR, 2) fwd_kernel(Ptrs P) {
;     ...
;             for (;;) {
;                 if (tid == 0) *qslot = (int)atomicAdd((unsigned*)(ws + 256 + 256 * xq), 1u);
;                 __syncthreads();
;                 const int idx = *qslot;
;                 __syncthreads();
;                 if (idx >= 128) break;
.LBB0_384:
	s_and_b64 vcc, exec, s[2:3]
	s_cbranch_vccnz .LBB0_381
	s_and_saveexec_b64 s[2:3], s[8:9]
	s_cbranch_execz .LBB0_389
	v_mov_b32_e32 v0, 0
	s_mov_b64 s[4:5], exec
	s_branch .LBB0_388
.LBB0_385:
	s_and_saveexec_b64 s[2:3], s[8:9]
	s_cbranch_execz .LBB0_389
	s_mov_b64 s[42:43], exec
	v_mbcnt_lo_u32_b32 v0, s42, 0
	v_mbcnt_hi_u32_b32 v0, s43, v0
	v_cmp_eq_u32_e32 vcc, 0, v0
	s_and_saveexec_b64 s[4:5], vcc
	s_cbranch_execz .LBB0_388
	s_bcnt1_i32_b64 s10, s[42:43]
	v_mov_b32_e32 v2, s10
	global_atomic_add v241, v1, v2, s[40:41] offset:256 sc0
.LBB0_388:
	s_or_b64 exec, exec, s[4:5]
	s_waitcnt vmcnt(0)
	v_readfirstlane_b32 s4, v241
	v_mov_b32_e32 v2, s50
	s_nop 0
	v_add_u32_e32 v0, s4, v0
	ds_write_b32 v2, v0

; __device__ __forceinline__ void unit(LAS unsigned char* lds, bf16_t* P1, const bf16_t* vaT, int b, int h, int qblk, float lam, const float* subln_w, const float* khalf) {
;     ...
;     asm volatile("s_waitcnt vmcnt(0) lgkmcnt(0)\n\ts_barrier" ::: "memory");
;     const float lt = l + __shfl_xor(l, 32); const float inv = 1.f / lt;
; __global__ void __launch_bounds__(NTHR, 2) fwd_kernel(Ptrs P) {
;     ...
;                 if (tid == 0) *qslot = (int)atomicAdd((unsigned*)(ws + 256 + 256 * xq), 1u);
;                 __syncthreads();
;                 const int idx = *qslot;
.LBB0_420:
	ds_bpermute_b32 v0, v115, v191
	s_waitcnt vmcnt(0) lgkmcnt(0)
	s_and_saveexec_b64 s[2:3], s[8:9]
	s_cbranch_execz .La_pf_skip
	v_mov_b32_e32 v240, 1
	global_atomic_add v241, v1, v240, s[40:41] offset:256 sc0
.La_pf_skip:
	s_or_b64 exec, exec, s[2:3]
	s_cmpk_gt_u32 s61, 0xff
	s_cbranch_scc1 .La_epi_noload
	global_load_dwordx4 v[236:239], v[118:119], off
	global_load_dwordx4 v[244:247], v[118:119], off offset:32
	global_load_dwordx4 v[248:251], v[118:119], off offset:64
	global_load_dwordx4 v[252:255], v[118:119], off offset:96
